# grid barrier: the per-CU L1 invalidate is issued before the arrival ticket (overlaps the ticket round trip and the release spin) instead of after the spin
# speedup vs baseline: 1.0189x; 1.0101x over previous
; DI unsigned xb_add(unsigned* p, unsigned v) { return __hip_atomic_fetch_add(p, v, __ATOMIC_RELAXED, __HIP_MEMORY_SCOPE_AGENT); }
; DI void xcd_barrier(const XcdBarrier& b) {
;     ...
;     unsigned long long ba_ = (unsigned long long)b.bar; unsigned bx = b.x; asm volatile("" : "+v"(bx));
;     unsigned* bar = (unsigned*)ba_;
;     __builtin_amdgcn_s_waitcnt(0);
;     unsigned nloc = b.st[0], nx = b.st[1];
;     if (nloc == 0u) { xcd_barrier_complete(bar, bx, nloc, nx); b.st[0] = nloc; b.st[1] = nx; }
;     const unsigned old = xb_add(&bar[XB_XSUB(bx)], 1u);
;     const unsigned gen = old / nloc;
;     if (old + 1u == (gen + 1u) * nloc) {
.LBB0_187:
	v_lshlrev_b32_e32 v4, 6, v1
	v_readlane_b32 s2, v249, 48
	v_add_u32_e32 v2, 0x500, v4
	v_mov_b32_e32 v3, 0
	v_readlane_b32 s3, v249, 49
	v_mov_b32_e32 v1, 1
	s_nop 0
	v_lshl_add_u64 v[6:7], v[2:3], 2, s[2:3]
	buffer_inv sc1
	global_atomic_add v1, v[6:7], v1, off sc0
	v_cvt_f32_u32_e32 v2, v0
	v_sub_u32_e32 v6, 0, v0
	v_rcp_iflag_f32_e32 v2, v2
	s_nop 0
	v_mul_f32_e32 v2, 0x4f7ffffe, v2
	v_cvt_u32_f32_e32 v2, v2
	v_mul_lo_u32 v6, v6, v2
	v_mul_hi_u32 v6, v2, v6
	v_add_u32_e32 v2, v2, v6
	s_waitcnt vmcnt(0)
	v_mul_hi_u32 v2, v1, v2
	v_mul_lo_u32 v6, v2, v0
	v_add_u32_e32 v7, 1, v1
	v_sub_u32_e32 v1, v1, v6
	v_add_u32_e32 v8, 1, v2
	v_cmp_ge_u32_e32 vcc, v1, v0
	v_sub_u32_e32 v6, v1, v0
	s_nop 0
	v_cndmask_b32_e32 v2, v2, v8, vcc
	v_cndmask_b32_e32 v1, v1, v6, vcc
	v_add_u32_e32 v6, 1, v2
	v_cmp_ge_u32_e32 vcc, v1, v0
	s_nop 1
	v_cndmask_b32_e32 v6, v2, v6, vcc
	v_mad_u64_u32 v[0:1], s[2:3], v0, v6, v[0:1]
	v_cmp_ne_u32_e32 vcc, v7, v0
	s_and_saveexec_b64 s[2:3], vcc
	s_xor_b64 s[2:3], exec, s[2:3]
	s_cbranch_execz .LBB0_201
	v_readlane_b32 s4, v249, 48
	v_add_u32_e32 v2, 0x900, v4
	v_readlane_b32 s5, v249, 49
	s_nop 1
	v_lshl_add_u64 v[0:1], v[2:3], 2, s[4:5]
	global_load_dword v2, v[0:1], off sc1
	s_waitcnt vmcnt(0)
	v_cmp_eq_u32_e32 vcc, v2, v6
	s_and_saveexec_b64 s[4:5], vcc
	s_cbranch_execz .LBB0_200
	s_add_u32 s6, s54, 0x329d8800
	s_addc_u32 s7, s55, 0
	s_mov_b32 s18, 1
	s_mov_b64 s[8:9], 0
	v_mov_b32_e32 v2, 0
	s_branch .LBB0_191

; DI unsigned xb_ld(unsigned* p)              { return __hip_atomic_load(p, __ATOMIC_RELAXED, __HIP_MEMORY_SCOPE_AGENT); }
; #define XB_SPIN(cond, bar) do { unsigned _sp = 0; while (cond) { __builtin_amdgcn_s_sleep(1); \
;     if ((++_sp & 255u) == 0u) { if (xb_ld(&(bar)[XB_TMO])) break; if (_sp > XB_SPIN_CAP) { atomicAdd(&(bar)[XB_TMO], 1u); break; } } } } while (0)
; DI void xcd_barrier(const XcdBarrier& b) {
;     ...
;     } else {
;       XB_SPIN(xb_ld(&bar[XB_XGEN(bx)]) == gen, bar);
;       __builtin_amdgcn_fence(__ATOMIC_ACQUIRE, "agent");
;       asm volatile("s_waitcnt vmcnt(0)" ::: "memory");
.LBB0_200:
	s_or_b64 exec, exec, s[4:5]
	s_waitcnt vmcnt(0) lgkmcnt(0)
	s_waitcnt vmcnt(0)

; DI unsigned xb_add(unsigned* p, unsigned v) { return __hip_atomic_fetch_add(p, v, __ATOMIC_RELAXED, __HIP_MEMORY_SCOPE_AGENT); }
; DI void xcd_barrier(const XcdBarrier& b) {
;     ...
;       __builtin_amdgcn_fence(__ATOMIC_ACQUIRE, "agent");
;       xb_add(&bar[XB_XGEN(bx)], 1u);
;       asm volatile("s_waitcnt vmcnt(0)" ::: "memory");
.LBB0_218:
	s_or_b64 exec, exec, s[2:3]
	v_readlane_b32 s2, v249, 48
	v_add_u32_e32 v0, 0x900, v4
	v_mov_b32_e32 v1, 0
	v_readlane_b32 s3, v249, 49
	v_mov_b32_e32 v2, 1
	s_waitcnt vmcnt(0)
	v_lshl_add_u64 v[0:1], v[0:1], 2, s[2:3]
	global_atomic_add v[0:1], v2, off
	s_waitcnt vmcnt(0)

; DI unsigned xb_add(unsigned* p, unsigned v) { return __hip_atomic_fetch_add(p, v, __ATOMIC_RELAXED, __HIP_MEMORY_SCOPE_AGENT); }
; DI void xcd_barrier(const XcdBarrier& b) {
;     ...
;     unsigned long long ba_ = (unsigned long long)b.bar; unsigned bx = b.x; asm volatile("" : "+v"(bx));
;     unsigned* bar = (unsigned*)ba_;
;     __builtin_amdgcn_s_waitcnt(0);
;     unsigned nloc = b.st[0], nx = b.st[1];
;     if (nloc == 0u) { xcd_barrier_complete(bar, bx, nloc, nx); b.st[0] = nloc; b.st[1] = nx; }
;     const unsigned old = xb_add(&bar[XB_XSUB(bx)], 1u);
;     const unsigned gen = old / nloc;
;     if (old + 1u == (gen + 1u) * nloc) {
.LBB0_704:
	v_lshlrev_b32_e32 v8, 6, v0
	v_readlane_b32 s2, v249, 48
	v_add_u32_e32 v0, 0x500, v8
	v_readlane_b32 s3, v249, 49
	s_nop 1
	v_lshl_add_u64 v[4:5], v[0:1], 2, s[2:3]
	v_mov_b32_e32 v0, 1
	buffer_inv sc1
	global_atomic_add v0, v[4:5], v0, off sc0
	v_cvt_f32_u32_e32 v4, v2
	v_sub_u32_e32 v5, 0, v2
	v_rcp_iflag_f32_e32 v4, v4
	s_nop 0
	v_mul_f32_e32 v4, 0x4f7ffffe, v4
	v_cvt_u32_f32_e32 v4, v4
	v_mul_lo_u32 v5, v5, v4
	v_mul_hi_u32 v5, v4, v5
	v_add_u32_e32 v4, v4, v5
	s_waitcnt vmcnt(0)
	v_mul_hi_u32 v4, v0, v4
	v_mul_lo_u32 v5, v4, v2
	v_sub_u32_e32 v5, v0, v5
	v_cmp_ge_u32_e32 vcc, v5, v2
	v_add_u32_e32 v6, 1, v4
	v_add_u32_e32 v0, 1, v0
	v_cndmask_b32_e32 v4, v4, v6, vcc
	v_sub_u32_e32 v6, v5, v2
	v_cndmask_b32_e32 v5, v5, v6, vcc
	v_cmp_ge_u32_e32 vcc, v5, v2
	v_add_u32_e32 v5, 1, v4
	s_nop 0
	v_cndmask_b32_e32 v4, v4, v5, vcc
	s_waitcnt lgkmcnt(0)
	v_mad_u64_u32 v[6:7], s[2:3], v2, v4, v[2:3]
	v_cmp_ne_u32_e32 vcc, v0, v6
	v_add_u32_e32 v0, 0x900, v8
	s_and_saveexec_b64 s[2:3], vcc
	s_xor_b64 s[2:3], exec, s[2:3]
	s_cbranch_execz .LBB0_718
	v_readlane_b32 s4, v249, 48
	v_readlane_b32 s5, v249, 49
	s_nop 1
	v_lshl_add_u64 v[2:3], v[0:1], 2, s[4:5]
	global_load_dword v0, v[2:3], off sc1
	s_waitcnt vmcnt(0)
	v_cmp_eq_u32_e32 vcc, v0, v4
	s_and_saveexec_b64 s[4:5], vcc
	s_cbranch_execz .LBB0_717
	s_mov_b32 s16, 1
	s_mov_b64 s[6:7], 0
	s_branch .LBB0_708

; DI unsigned xb_ld(unsigned* p)              { return __hip_atomic_load(p, __ATOMIC_RELAXED, __HIP_MEMORY_SCOPE_AGENT); }
; #define XB_SPIN(cond, bar) do { unsigned _sp = 0; while (cond) { __builtin_amdgcn_s_sleep(1); \
;     if ((++_sp & 255u) == 0u) { if (xb_ld(&(bar)[XB_TMO])) break; if (_sp > XB_SPIN_CAP) { atomicAdd(&(bar)[XB_TMO], 1u); break; } } } } while (0)
; DI void xcd_barrier(const XcdBarrier& b) {
;     ...
;     } else {
;       XB_SPIN(xb_ld(&bar[XB_XGEN(bx)]) == gen, bar);
;       __builtin_amdgcn_fence(__ATOMIC_ACQUIRE, "agent");
;       asm volatile("s_waitcnt vmcnt(0)" ::: "memory");
.LBB0_717:
	s_or_b64 exec, exec, s[4:5]
	s_waitcnt vmcnt(0)
	s_waitcnt vmcnt(0)

; DI unsigned xb_add(unsigned* p, unsigned v) { return __hip_atomic_fetch_add(p, v, __ATOMIC_RELAXED, __HIP_MEMORY_SCOPE_AGENT); }
; DI void xcd_barrier(const XcdBarrier& b) {
;     ...
;       __builtin_amdgcn_fence(__ATOMIC_ACQUIRE, "agent");
;       xb_add(&bar[XB_XGEN(bx)], 1u);
;       asm volatile("s_waitcnt vmcnt(0)" ::: "memory");
.LBB0_735:
	s_or_b64 exec, exec, s[2:3]
	v_readlane_b32 s2, v249, 48
	v_readlane_b32 s3, v249, 49
	s_waitcnt vmcnt(0)
	v_lshl_add_u64 v[2:3], v[0:1], 2, s[2:3]
	v_mov_b32_e32 v0, 1
	global_atomic_add v[2:3], v0, off
	s_waitcnt vmcnt(0)

; DI unsigned xb_add(unsigned* p, unsigned v) { return __hip_atomic_fetch_add(p, v, __ATOMIC_RELAXED, __HIP_MEMORY_SCOPE_AGENT); }
; DI void xcd_barrier(const XcdBarrier& b) {
;     ...
;     unsigned long long ba_ = (unsigned long long)b.bar; unsigned bx = b.x; asm volatile("" : "+v"(bx));
;     unsigned* bar = (unsigned*)ba_;
;     __builtin_amdgcn_s_waitcnt(0);
;     unsigned nloc = b.st[0], nx = b.st[1];
;     if (nloc == 0u) { xcd_barrier_complete(bar, bx, nloc, nx); b.st[0] = nloc; b.st[1] = nx; }
;     const unsigned old = xb_add(&bar[XB_XSUB(bx)], 1u);
;     const unsigned gen = old / nloc;
;     if (old + 1u == (gen + 1u) * nloc) {
.LBB0_1623:
	v_lshlrev_b32_e32 v8, 6, v0
	v_readlane_b32 s2, v249, 48
	v_add_u32_e32 v0, 0x500, v8
	v_readlane_b32 s3, v249, 49
	s_nop 1
	v_lshl_add_u64 v[4:5], v[0:1], 2, s[2:3]
	v_mov_b32_e32 v0, 1
	buffer_inv sc1
	global_atomic_add v0, v[4:5], v0, off sc0
	v_cvt_f32_u32_e32 v4, v2
	v_sub_u32_e32 v5, 0, v2
	v_rcp_iflag_f32_e32 v4, v4
	s_nop 0
	v_mul_f32_e32 v4, 0x4f7ffffe, v4
	v_cvt_u32_f32_e32 v4, v4
	v_mul_lo_u32 v5, v5, v4
	v_mul_hi_u32 v5, v4, v5
	v_add_u32_e32 v4, v4, v5
	s_waitcnt vmcnt(0)
	v_mul_hi_u32 v4, v0, v4
	v_mul_lo_u32 v5, v4, v2
	v_sub_u32_e32 v5, v0, v5
	v_cmp_ge_u32_e32 vcc, v5, v2
	v_add_u32_e32 v6, 1, v4
	v_add_u32_e32 v0, 1, v0
	v_cndmask_b32_e32 v4, v4, v6, vcc
	v_sub_u32_e32 v6, v5, v2
	v_cndmask_b32_e32 v5, v5, v6, vcc
	v_cmp_ge_u32_e32 vcc, v5, v2
	v_add_u32_e32 v5, 1, v4
	s_nop 0
	v_cndmask_b32_e32 v4, v4, v5, vcc
	s_waitcnt lgkmcnt(0)
	v_mad_u64_u32 v[6:7], s[2:3], v2, v4, v[2:3]
	v_cmp_ne_u32_e32 vcc, v0, v6
	v_add_u32_e32 v0, 0x900, v8
	s_and_saveexec_b64 s[2:3], vcc
	s_xor_b64 s[2:3], exec, s[2:3]
	s_cbranch_execz .LBB0_1637
	v_readlane_b32 s4, v249, 48
	v_readlane_b32 s5, v249, 49
	s_nop 1
	v_lshl_add_u64 v[2:3], v[0:1], 2, s[4:5]
	global_load_dword v0, v[2:3], off sc1
	s_waitcnt vmcnt(0)
	v_cmp_eq_u32_e32 vcc, v0, v4
	s_and_saveexec_b64 s[4:5], vcc
	s_cbranch_execz .LBB0_1636
	s_mov_b32 s18, 1
	s_mov_b64 s[8:9], 0
	s_branch .LBB0_1627
